# stages 2+3 merged: grid barrier replaced by m2->m3 completion counter (write-through m2 stores, release/acquire); re-measure
# speedup vs baseline: 1.0707x; 1.0042x over previous
.LBB0_692:
	s_or_b64 exec, exec, s[0:1]
	v_readlane_b32 s0, v248, 16
	v_readlane_b32 s1, v248, 17
	s_and_b64 s[0:1], s[0:1], exec
	s_cselect_b32 s11, 16, 18
	s_lshl_b32 s44, s11, 6
	s_addk_i32 s44, 0x400
	s_add_i32 s10, 0, 0x13ff8
	v_readlane_b32 s2, v249, 56
	s_cmp_lg_u32 s10, -1
	v_readlane_b32 s3, v249, 57
	s_cselect_b32 s0, s10, 0
	s_cselect_b32 s1, s3, 0
	v_mov_b32_e32 v0, s0
	v_mov_b32_e32 v1, s1
	s_waitcnt lgkmcnt(0)
	s_barrier
	flat_load_dword v0, v[0:1] sc0 sc1
	s_waitcnt vmcnt(0) lgkmcnt(0)
	v_readfirstlane_b32 s48, v0
	s_cmp_ge_i32 s48, s44
	s_cbranch_scc1 .LBB0_763
	v_mov_b32_e32 v253, 0
	v_cvt_f32_u32_e32 v0, s11
	v_readlane_b32 s0, v248, 11
	s_lshl_b32 s45, s0, 3
	s_sub_i32 s0, 0, s11
	v_rcp_iflag_f32_e32 v0, v0
	s_nop 0
	v_mul_f32_e32 v0, 0x4f7ffffe, v0
	v_cvt_u32_f32_e32 v0, v0
	s_nop 0
	v_readfirstlane_b32 s1, v0
	s_mul_i32 s0, s0, s1
	s_mul_hi_u32 s0, s1, s0
	s_add_i32 s47, s1, s0
	s_branch .LBB0_696

.LBB0_723:
	s_and_b64 vcc, exec, s[0:1]
	s_cbranch_vccz .LBB0_760
	v_mov_b32_e32 v253, 1
	s_and_b32 s12, s48, 15
	v_mov_b32_e32 v10, v162
	s_lshl_b32 s0, s12, 10
	s_ashr_i32 s4, s48, 4
	v_lshl_add_u32 v0, v10, 2, s0
	v_readlane_b32 s0, v249, 27
	v_ashrrev_i32_e32 v1, 31, v0
	v_readlane_b32 s1, v249, 28
	s_cmp_eq_u32 s12, 0
	s_mul_i32 s4, s4, 18
	v_lshl_add_u64 v[4:5], v[0:1], 1, s[0:1]
	s_cselect_b64 s[2:3], -1, 0
	s_bfe_u32 s0, s48, 0x10004
	s_or_b32 s6, s0, s4
	s_movk_i32 s8, 0x80
	s_ashr_i32 s7, s6, 31
	v_cmp_gt_i32_e64 s[38:39], s8, v10
	v_readlane_b32 s8, v249, 29
	s_lshl_b64 s[0:1], s[6:7], 15
	v_ashrrev_i32_e32 v11, 31, v10
	v_readlane_b32 s9, v249, 30
	s_cmp_lg_u32 s12, 0
	v_cmp_eq_u32_e64 s[40:41], 0, v10
	v_lshl_add_u64 v[6:7], v[10:11], 2, s[8:9]
	v_lshl_add_u64 v[2:3], v[4:5], 0, s[0:1]
	global_store_dwordx2 v[2:3], v[240:241], off sc0 sc1
	s_cbranch_scc1 .LBB0_730
	s_and_saveexec_b64 s[0:1], s[38:39]
	s_cbranch_execz .LBB0_727
	s_lshl_b64 s[12:13], s[6:7], 9
	v_lshl_add_u64 v[2:3], v[6:7], 0, s[12:13]
	global_store_dword v[2:3], v97, off sc0 sc1
.LBB0_727:
	s_or_b64 exec, exec, s[0:1]
	s_and_saveexec_b64 s[0:1], s[40:41]
	s_cbranch_execz .LBB0_729
	s_lshl_b64 s[12:13], s[6:7], 2
	s_add_u32 s12, s78, s12
	s_addc_u32 s13, s72, s13
	global_store_dword v97, v97, s[12:13] sc0 sc1

.LBB0_732:
	s_or_b64 exec, exec, s[12:13]
	s_xor_b32 s6, s6, 1
	s_ashr_i32 s7, s6, 31
	s_waitcnt vmcnt(0)
	v_pk_fma_f32 v[14:15], v[0:1], v[16:17], v[18:19] op_sel_hi:[1,0,0]
	v_pk_fma_f32 v[16:17], v[2:3], v[16:17], v[18:19] op_sel_hi:[1,0,0]
	s_lshl_b64 s[12:13], s[6:7], 15
	v_cvt_pk_bf16_f32 v0, v14, v15
	v_cvt_pk_bf16_f32 v1, v16, v17
	v_lshl_add_u64 v[2:3], v[4:5], 0, s[12:13]
	global_store_dwordx2 v[2:3], v[0:1], off sc0 sc1
	v_cndmask_b32_e64 v0, 0, 1, s[2:3]
	v_cmp_ne_u32_e64 s[42:43], 1, v0
	s_andn2_b64 vcc, exec, s[2:3]
	s_cbranch_vccnz .LBB0_738
	s_and_saveexec_b64 s[2:3], s[38:39]
	s_cbranch_execz .LBB0_735
	s_lshl_b64 s[12:13], s[6:7], 9
	v_lshl_add_u64 v[0:1], v[6:7], 0, s[12:13]
	global_store_dword v[0:1], v12, off sc0 sc1
.LBB0_735:
	s_or_b64 exec, exec, s[2:3]
	s_and_saveexec_b64 s[2:3], s[40:41]
	s_cbranch_execz .LBB0_737
	s_lshl_b64 s[12:13], s[6:7], 2
	s_add_u32 s12, s78, s12
	s_addc_u32 s13, s72, s13
	global_store_dword v97, v13, s[12:13] sc0 sc1

.LBB0_743:
	s_add_i32 s12, s49, 1
	s_and_b64 s[6:7], s[2:3], exec
	s_cselect_b32 s6, s48, s12
	s_add_i32 s6, s6, s4
	s_ashr_i32 s7, s6, 31
	s_lshl_b64 s[12:13], s[6:7], 15
	v_cvt_pk_bf16_f32 v0, v14, v15
	v_cvt_pk_bf16_f32 v1, v16, v17
	v_lshl_add_u64 v[2:3], v[4:5], 0, s[12:13]
	s_and_b64 vcc, exec, s[42:43]
	global_store_dwordx2 v[2:3], v[0:1], off sc0 sc1
	s_cbranch_vccnz .LBB0_749
	s_and_saveexec_b64 s[12:13], s[38:39]
	s_cbranch_execz .LBB0_746
	s_lshl_b64 s[50:51], s[6:7], 9
	v_lshl_add_u64 v[0:1], v[6:7], 0, s[50:51]
	global_store_dword v[0:1], v12, off sc0 sc1
.LBB0_746:
	s_or_b64 exec, exec, s[12:13]
	s_and_saveexec_b64 s[12:13], s[40:41]
	s_cbranch_execz .LBB0_748
	s_lshl_b64 s[50:51], s[6:7], 2
	s_add_u32 s50, s78, s50
	s_addc_u32 s51, s72, s51
	global_store_dword v97, v23, s[50:51] sc0 sc1

.LBB0_751:
	s_or_b64 exec, exec, s[12:13]
	s_add_i32 s12, s48, 1
	s_and_b64 s[6:7], s[2:3], exec
	s_cselect_b32 s6, s12, s49
	s_waitcnt vmcnt(0)
	v_pk_mul_f32 v[0:1], v[0:1], v[22:23] op_sel_hi:[1,0]
	s_add_i32 s6, s6, s4
	v_pk_fma_f32 v[18:19], v[14:15], v[20:21], v[0:1] op_sel_hi:[1,0,1]
	v_pk_mul_f32 v[0:1], v[2:3], v[22:23] op_sel_hi:[1,0]
	s_ashr_i32 s7, s6, 31
	v_pk_fma_f32 v[20:21], v[16:17], v[20:21], v[0:1] op_sel_hi:[1,0,1]
	s_lshl_b64 s[12:13], s[6:7], 15
	v_cvt_pk_bf16_f32 v0, v18, v19
	v_cvt_pk_bf16_f32 v1, v20, v21
	v_lshl_add_u64 v[2:3], v[4:5], 0, s[12:13]
	s_and_b64 vcc, exec, s[42:43]
	global_store_dwordx2 v[2:3], v[0:1], off sc0 sc1
	s_cbranch_vccz .LBB0_753
	s_cmp_eq_u32 s48, 16
	s_mov_b64 s[12:13], -1
	s_cbranch_scc1 .LBB0_742
	s_branch .LBB0_758
.LBB0_753:
	s_and_saveexec_b64 s[12:13], s[38:39]
	s_cbranch_execz .LBB0_755
	s_lshl_b64 s[50:51], s[6:7], 9
	v_lshl_add_u64 v[0:1], v[6:7], 0, s[50:51]
	global_store_dword v[0:1], v12, off sc0 sc1
.LBB0_755:
	s_or_b64 exec, exec, s[12:13]
	s_and_saveexec_b64 s[12:13], s[40:41]
	s_cbranch_execz .LBB0_757
	s_lshl_b64 s[50:51], s[6:7], 2
	s_add_u32 s50, s78, s50
	s_addc_u32 s51, s72, s51
	global_store_dword v97, v24, s[50:51] sc0 sc1

.LBB0_760:
	v_readfirstlane_b32 s100, v253
	s_cmp_eq_u32 s100, 0
	s_cbranch_scc1 .Lm2rel_a
	s_waitcnt vmcnt(0)
.Lm2rel_a:
	s_barrier
	v_mov_b32_e32 v253, 0
	s_mov_b64 s[0:1], exec
	v_readlane_b32 s2, v251, 0
	v_readlane_b32 s3, v251, 1
	s_and_b64 s[2:3], s[0:1], s[2:3]
	s_mov_b64 exec, s[2:3]
	s_cbranch_execz .LBB0_695
	s_mov_b64 s[6:7], exec
	v_mbcnt_lo_u32_b32 v0, s6, 0
	v_mbcnt_hi_u32_b32 v0, s7, v0
	v_cmp_eq_u32_e32 vcc, 0, v0
	s_and_saveexec_b64 s[2:3], vcc
	s_cbranch_execz .LBB0_694
	s_bcnt1_i32_b64 s4, s[6:7]
	v_readlane_b32 s6, v248, 20
	v_mov_b32_e32 v1, s4
	v_readlane_b32 s7, v248, 21
	s_nop 4
	s_cmp_eq_u32 s100, 0
	s_cbranch_scc1 .Lm2rel_b
	s_waitcnt vmcnt(0)
	v_mov_b32_e32 v2, 1
	global_atomic_add v97, v2, s[6:7] offset:96
.Lm2rel_b:
	global_atomic_add v1, v97, v1, s[6:7] offset:32 sc0
	s_branch .LBB0_694
.LBB0_763:
	s_waitcnt vmcnt(0)
	s_barrier
	s_mov_b64 s[0:1], exec
	v_readlane_b32 s2, v251, 0
	v_readlane_b32 s3, v251, 1
	s_and_b64 s[2:3], s[0:1], s[2:3]
	s_mov_b64 exec, s[2:3]
	s_branch .LBB0_811
	v_readlane_b32 s2, v249, 49
	s_waitcnt vmcnt(0) expcnt(0) lgkmcnt(0)
	s_nop 0
	v_mov_b32_e32 v0, s2
	ds_read_b32 v2, v0
	v_readlane_b32 s2, v249, 50
	s_waitcnt lgkmcnt(0)
	v_cmp_ne_u32_e32 vcc, 0, v2
	v_mov_b32_e32 v0, s2
	ds_read_b32 v0, v0
	s_cbranch_vccnz .LBB0_779
	s_mov_b32 s4, 1
	s_branch .LBB0_767

.LBB0_922:
	s_and_b64 vcc, exec, s[0:1]
	s_cbranch_vccz .LBB0_1113
	v_cmp_eq_u32_e64 s[100:101], 0, v162
	s_and_saveexec_b64 s[100:101], s[100:101]
	s_cbranch_execz .Lm3acq_done
	v_readlane_b32 s0, v248, 20
	v_readlane_b32 s1, v248, 21
	s_movk_i32 s2, 0x4000
	s_nop 4
.Lm3acq_spin:
	global_load_dword v252, v97, s[0:1] offset:96 sc1
	s_waitcnt vmcnt(0)
	v_readfirstlane_b32 s3, v252
	s_cmpk_ge_u32 s3, 0x400
	s_cbranch_scc1 .Lm3acq_ok
	s_sleep 2
	s_add_i32 s2, s2, -1
	s_cmp_lg_u32 s2, 0
	s_cbranch_scc1 .Lm3acq_spin

.Lm3acq_done:
	s_mov_b64 exec, s[100:101]
	s_barrier
	v_readlane_b32 s0, v251, 58
	s_ashr_i32 s0, s6, 31
	v_readlane_b32 s1, v248, 29
	s_xor_b32 s0, s0, s1
	s_abs_i32 s1, s6
	v_readlane_b32 s2, v248, 31
	s_mul_hi_u32 s2, s1, s2
	v_readlane_b32 s7, v248, 30
	s_mul_i32 s3, s2, s7
	s_sub_i32 s1, s1, s3
	s_add_i32 s3, s2, 1
	s_sub_i32 s4, s1, s7
	s_cmp_ge_u32 s1, s7
	s_cselect_b32 s2, s3, s2
	s_cselect_b32 s1, s4, s1
	s_add_i32 s3, s2, 1
	s_cmp_ge_u32 s1, s7
	s_cselect_b32 s1, s3, s2
	s_xor_b32 s1, s1, s0
	s_sub_i32 s0, s1, s0
	s_mul_i32 s1, s0, s60
	s_sub_i32 s60, s6, s1
	s_add_i32 s60, s60, s61
	s_ashr_i32 s4, s0, 2
	s_and_b32 s11, s0, 3
	s_lshl_b32 s0, s60, 7
	s_cmp_lt_i32 s60, 2
	s_movk_i32 s2, 0xff00
	s_cselect_b32 s1, 8, 11
	s_cselect_b32 s2, 0x4000, s2
	s_mov_b32 s9, s61
	s_lshl_b32 s1, s4, s1
	s_add_i32 s61, s0, s2
	s_add_i32 s61, s61, s1
	s_mul_i32 s1, s61, 0x3600
	v_readlane_b32 s2, v249, 7
	s_mul_hi_i32 s0, s61, 0x3600
	v_readlane_b32 s3, v249, 8
	s_add_u32 s6, s2, s1
	s_addc_u32 s7, s3, s0
	s_lshl_b32 s0, s11, 8
	v_mov_b32_e32 v0, v162
	s_add_u32 s70, s6, s0
	v_mov_b32_e32 v1, v162
	s_movk_i32 s0, 0x800
	s_barrier
	s_addc_u32 s71, s7, 0
	s_nop 0
	v_cmp_gt_i32_e32 vcc, s0, v1
	s_and_saveexec_b64 s[0:1], vcc
	s_cbranch_execz .LBB0_926
	v_readlane_b32 s2, v249, 53
	v_lshlrev_b32_e32 v3, 3, v1
	s_nop 0
	v_lshl_add_u32 v2, v1, 4, s2
	s_mov_b64 s[2:3], 0
